# G3 K-loop: first 8 MFMAs of every 32-MFMA block issued before the block's leading barrier (the loading half's idle tail does matrix work)
# baseline (speedup 1.0000x reference)
.LBB0_959:
	s_ashr_i32 s29, s28, 31
	s_lshl_b64 s[38:39], s[28:29], 19
	s_add_u32 s38, s16, s38
	s_addc_u32 s39, s17, s39
	s_and_b64 s[40:41], s[0:1], exec
	s_cselect_b32 s29, s39, s15
	s_cselect_b32 s54, s38, s14
	s_ashr_i32 s13, s12, 31
	s_lshl_b64 s[40:41], s[12:13], 19
	s_add_u32 s40, s18, s40
	s_addc_u32 s41, s19, s41
	s_and_b64 s[46:47], s[0:1], exec
	s_cselect_b32 s13, s41, s43
	s_cselect_b32 s55, s40, s42
	s_add_u32 s60, s42, 0x100
	s_addc_u32 s61, s43, 0
	s_add_u32 s42, s14, 0x40080
	s_addc_u32 s43, s15, 0
	s_mov_b32 s63, -2
	s_add_u32 s14, s42, 0xfffc0080
	s_addc_u32 s15, s43, -1
	s_add_i32 s24, 0, 0x10000
	s_cmp_eq_u32 s63, 12
	s_cselect_b32 s47, s29, s15
	s_cselect_b32 s46, s54, s14
	s_cselect_b32 s15, s13, s61
	s_cselect_b32 s14, s55, s60
	s_add_i32 s25, 0, 0x14000
	v_add_u32_e32 v172, s24, v145
	v_add_u32_e32 v188, s25, v145
	ds_read_b128 v[140:143], v172
	ds_read_b128 v[148:151], v172 offset:1024
	ds_read_b128 v[152:155], v172 offset:2048
	ds_read_b128 v[172:175], v172 offset:3072
	ds_read_b128 v[176:179], v188
	ds_read_b128 v[180:183], v188 offset:1024
	ds_read_b128 v[184:187], v188 offset:2048
	ds_read_b128 v[188:191], v188 offset:3072
	v_lshl_add_u64 v[192:193], s[42:43], 0, v[138:139]
	s_add_i32 m0, s21, 0xc000
	ds_read_b128 v[200:203], v147
	ds_read_b128 v[204:207], v147 offset:1024
	ds_read_b128 v[208:211], v147 offset:2048
	ds_read_b128 v[212:215], v147 offset:3072
	ds_read_b128 v[216:219], v147 offset:4096
	ds_read_b128 v[220:223], v147 offset:5120
	ds_read_b128 v[224:227], v147 offset:6144
	ds_read_b128 v[228:231], v147 offset:7168
	global_load_lds_dwordx4 v[192:193], off
	v_lshl_add_u64 v[192:193], s[42:43], 0, v[136:137]
	s_add_i32 m0, s21, 0xe000
	s_nop 0
	global_load_lds_dwordx4 v[192:193], off
	s_waitcnt vmcnt(8)
	s_waitcnt lgkmcnt(0)
	v_mfma_f32_16x16x32_bf16 v[124:127], v[140:143], v[200:203], 0
	v_mfma_f32_16x16x32_bf16 v[116:119], v[152:155], v[200:203], 0
	v_mfma_f32_16x16x32_bf16 v[108:111], v[140:143], v[208:211], 0
	v_mfma_f32_16x16x32_bf16 v[104:107], v[152:155], v[208:211], 0
	v_mfma_f32_16x16x32_bf16 v[92:95], v[140:143], v[216:219], 0
	v_mfma_f32_16x16x32_bf16 v[88:91], v[152:155], v[216:219], 0
	v_mfma_f32_16x16x32_bf16 v[76:79], v[140:143], v[224:227], 0
	v_mfma_f32_16x16x32_bf16 v[72:75], v[152:155], v[224:227], 0
	s_barrier
	s_setprio 1
	s_waitcnt lgkmcnt(0)
	v_mfma_f32_16x16x32_bf16 v[124:127], v[148:151], v[204:207], v[124:127]
	v_mfma_f32_16x16x32_bf16 v[116:119], v[172:175], v[204:207], v[116:119]
	v_mfma_f32_16x16x32_bf16 v[108:111], v[148:151], v[212:215], v[108:111]
	v_mfma_f32_16x16x32_bf16 v[104:107], v[172:175], v[212:215], v[104:107]
	v_mfma_f32_16x16x32_bf16 v[92:95], v[148:151], v[220:223], v[92:95]
	v_mfma_f32_16x16x32_bf16 v[88:91], v[172:175], v[220:223], v[88:91]
	v_mfma_f32_16x16x32_bf16 v[76:79], v[148:151], v[228:231], v[76:79]
	v_mfma_f32_16x16x32_bf16 v[72:75], v[172:175], v[228:231], v[72:75]
	s_setprio 0
	s_setprio 1
	v_mfma_f32_16x16x32_bf16 v[128:131], v[176:179], v[200:203], 0
	v_mfma_f32_16x16x32_bf16 v[120:123], v[184:187], v[200:203], 0
	v_mfma_f32_16x16x32_bf16 v[112:115], v[176:179], v[208:211], 0
	v_mfma_f32_16x16x32_bf16 v[100:103], v[184:187], v[208:211], 0
	v_mfma_f32_16x16x32_bf16 v[96:99], v[176:179], v[216:219], 0
	v_mfma_f32_16x16x32_bf16 v[84:87], v[184:187], v[216:219], 0
	v_mfma_f32_16x16x32_bf16 v[80:83], v[176:179], v[224:227], 0
	v_mfma_f32_16x16x32_bf16 v[68:71], v[184:187], v[224:227], 0
	v_mfma_f32_16x16x32_bf16 v[128:131], v[180:183], v[204:207], v[128:131]
	v_mfma_f32_16x16x32_bf16 v[120:123], v[188:191], v[204:207], v[120:123]
	v_mfma_f32_16x16x32_bf16 v[112:115], v[180:183], v[212:215], v[112:115]
	v_mfma_f32_16x16x32_bf16 v[100:103], v[188:191], v[212:215], v[100:103]
	v_mfma_f32_16x16x32_bf16 v[96:99], v[180:183], v[220:223], v[96:99]
	v_mfma_f32_16x16x32_bf16 v[84:87], v[188:191], v[220:223], v[84:87]
	v_mfma_f32_16x16x32_bf16 v[80:83], v[180:183], v[228:231], v[80:83]
	v_mfma_f32_16x16x32_bf16 v[68:71], v[188:191], v[228:231], v[68:71]
	s_setprio 0
	s_barrier
	s_add_i32 s24, s24, s20
	v_lshl_add_u64 v[192:193], s[14:15], 0, v[2:3]
	s_mov_b32 m0, s24
	ds_read_b128 v[200:203], v147 offset:16384
	ds_read_b128 v[204:207], v147 offset:17408
	ds_read_b128 v[208:211], v147 offset:18432
	ds_read_b128 v[212:215], v147 offset:19456
	ds_read_b128 v[216:219], v147 offset:20480
	ds_read_b128 v[220:223], v147 offset:21504
	ds_read_b128 v[224:227], v147 offset:22528
	ds_read_b128 v[228:231], v147 offset:23552
	global_load_lds_dwordx4 v[192:193], off
	s_add_i32 m0, s24, 0x2000
	s_add_u32 s64, s14, 0x40000
	v_lshl_add_u64 v[232:233], s[14:15], 0, v[0:1]
	s_addc_u32 s65, s15, 0
	s_add_i32 s24, s25, s20
	global_load_lds_dwordx4 v[232:233], off
	v_lshl_add_u64 v[234:235], s[64:65], 0, v[2:3]
	s_mov_b32 m0, s24
	v_lshl_add_u64 v[236:237], s[46:47], 0, v[132:133]
	global_load_lds_dwordx4 v[234:235], off
	v_lshl_add_u64 v[234:235], s[64:65], 0, v[0:1]
	s_add_i32 m0, s24, 0x2000
	s_nop 0
	global_load_lds_dwordx4 v[234:235], off
	v_lshl_add_u64 v[234:235], s[46:47], 0, v[134:135]
	s_mov_b32 m0, s21
	s_nop 0
	global_load_lds_dwordx4 v[234:235], off
	s_mov_b32 m0, s22
	s_nop 0
	global_load_lds_dwordx4 v[236:237], off
	s_waitcnt vmcnt(8)
	s_waitcnt lgkmcnt(0)
	v_mfma_f32_16x16x32_bf16 v[60:63], v[140:143], v[200:203], 0
	v_mfma_f32_16x16x32_bf16 v[56:59], v[152:155], v[200:203], 0
	v_mfma_f32_16x16x32_bf16 v[44:47], v[140:143], v[208:211], 0
	v_mfma_f32_16x16x32_bf16 v[40:43], v[152:155], v[208:211], 0
	v_mfma_f32_16x16x32_bf16 v[28:31], v[140:143], v[216:219], 0
	v_mfma_f32_16x16x32_bf16 v[24:27], v[152:155], v[216:219], 0
	v_mfma_f32_16x16x32_bf16 v[12:15], v[140:143], v[224:227], 0
	v_mfma_f32_16x16x32_bf16 v[4:7], v[152:155], v[224:227], 0
	s_barrier
	s_setprio 1
	s_waitcnt lgkmcnt(0)
	v_mfma_f32_16x16x32_bf16 v[60:63], v[148:151], v[204:207], v[60:63]
	v_mfma_f32_16x16x32_bf16 v[56:59], v[172:175], v[204:207], v[56:59]
	v_mfma_f32_16x16x32_bf16 v[44:47], v[148:151], v[212:215], v[44:47]
	v_mfma_f32_16x16x32_bf16 v[40:43], v[172:175], v[212:215], v[40:43]
	v_mfma_f32_16x16x32_bf16 v[28:31], v[148:151], v[220:223], v[28:31]
	v_mfma_f32_16x16x32_bf16 v[24:27], v[172:175], v[220:223], v[24:27]
	v_mfma_f32_16x16x32_bf16 v[12:15], v[148:151], v[228:231], v[12:15]
	v_mfma_f32_16x16x32_bf16 v[4:7], v[172:175], v[228:231], v[4:7]
	s_setprio 0
	s_setprio 1
	v_mfma_f32_16x16x32_bf16 v[64:67], v[176:179], v[200:203], 0
	v_mfma_f32_16x16x32_bf16 v[52:55], v[184:187], v[200:203], 0
	v_mfma_f32_16x16x32_bf16 v[48:51], v[176:179], v[208:211], 0
	v_mfma_f32_16x16x32_bf16 v[36:39], v[184:187], v[208:211], 0
	v_mfma_f32_16x16x32_bf16 v[32:35], v[176:179], v[216:219], 0
	v_mfma_f32_16x16x32_bf16 v[20:23], v[184:187], v[216:219], 0
	v_mfma_f32_16x16x32_bf16 v[16:19], v[176:179], v[224:227], 0
	v_mfma_f32_16x16x32_bf16 v[8:11], v[184:187], v[224:227], 0
	v_mfma_f32_16x16x32_bf16 v[64:67], v[180:183], v[204:207], v[64:67]
	v_mfma_f32_16x16x32_bf16 v[52:55], v[188:191], v[204:207], v[52:55]
	v_mfma_f32_16x16x32_bf16 v[48:51], v[180:183], v[212:215], v[48:51]
	v_mfma_f32_16x16x32_bf16 v[36:39], v[188:191], v[212:215], v[36:39]
	v_mfma_f32_16x16x32_bf16 v[32:35], v[180:183], v[220:223], v[32:35]
	v_mfma_f32_16x16x32_bf16 v[20:23], v[188:191], v[220:223], v[20:23]
	v_mfma_f32_16x16x32_bf16 v[16:19], v[180:183], v[228:231], v[16:19]
	v_mfma_f32_16x16x32_bf16 v[8:11], v[188:191], v[228:231], v[8:11]
	s_setprio 0
	s_barrier
	s_add_i32 s24, 0, 0x18000
	s_add_i32 s25, 0, 0x1c000
	v_add_u32_e32 v172, s24, v145
	v_add_u32_e32 v188, s25, v145
	ds_read_b128 v[140:143], v172
	ds_read_b128 v[148:151], v172 offset:1024
	ds_read_b128 v[152:155], v172 offset:2048
	ds_read_b128 v[172:175], v172 offset:3072
	ds_read_b128 v[176:179], v188
	ds_read_b128 v[180:183], v188 offset:1024
	ds_read_b128 v[184:187], v188 offset:2048
	ds_read_b128 v[188:191], v188 offset:3072
	s_add_u32 s46, s46, 0x40000
	s_addc_u32 s47, s47, 0
	s_mov_b32 m0, s23
	v_lshl_add_u64 v[238:239], s[46:47], 0, v[134:135]
	ds_read_b128 v[200:203], v147 offset:32768
	ds_read_b128 v[204:207], v147 offset:33792
	ds_read_b128 v[208:211], v147 offset:34816
	ds_read_b128 v[212:215], v147 offset:35840
	ds_read_b128 v[216:219], v147 offset:36864
	ds_read_b128 v[220:223], v147 offset:37888
	ds_read_b128 v[224:227], v147 offset:38912
	ds_read_b128 v[228:231], v147 offset:39936
	global_load_lds_dwordx4 v[238:239], off
	v_lshl_add_u64 v[238:239], s[46:47], 0, v[132:133]
	s_mov_b32 m0, s45
	s_nop 0
	global_load_lds_dwordx4 v[238:239], off
	s_waitcnt vmcnt(8)
	s_waitcnt lgkmcnt(0)
	v_mfma_f32_16x16x32_bf16 v[124:127], v[140:143], v[200:203], v[124:127]
	v_mfma_f32_16x16x32_bf16 v[116:119], v[152:155], v[200:203], v[116:119]
	v_mfma_f32_16x16x32_bf16 v[108:111], v[140:143], v[208:211], v[108:111]
	v_mfma_f32_16x16x32_bf16 v[104:107], v[152:155], v[208:211], v[104:107]
	v_mfma_f32_16x16x32_bf16 v[92:95], v[140:143], v[216:219], v[92:95]
	v_mfma_f32_16x16x32_bf16 v[88:91], v[152:155], v[216:219], v[88:91]
	v_mfma_f32_16x16x32_bf16 v[76:79], v[140:143], v[224:227], v[76:79]
	v_mfma_f32_16x16x32_bf16 v[72:75], v[152:155], v[224:227], v[72:75]
	s_barrier
	s_setprio 1
	s_waitcnt lgkmcnt(0)
	v_mfma_f32_16x16x32_bf16 v[124:127], v[148:151], v[204:207], v[124:127]
	v_mfma_f32_16x16x32_bf16 v[116:119], v[172:175], v[204:207], v[116:119]
	v_mfma_f32_16x16x32_bf16 v[108:111], v[148:151], v[212:215], v[108:111]
	v_mfma_f32_16x16x32_bf16 v[104:107], v[172:175], v[212:215], v[104:107]
	v_mfma_f32_16x16x32_bf16 v[92:95], v[148:151], v[220:223], v[92:95]
	v_mfma_f32_16x16x32_bf16 v[88:91], v[172:175], v[220:223], v[88:91]
	v_mfma_f32_16x16x32_bf16 v[76:79], v[148:151], v[228:231], v[76:79]
	v_mfma_f32_16x16x32_bf16 v[72:75], v[172:175], v[228:231], v[72:75]
	s_setprio 0
	s_setprio 1
	v_mfma_f32_16x16x32_bf16 v[128:131], v[176:179], v[200:203], v[128:131]
	v_mfma_f32_16x16x32_bf16 v[120:123], v[184:187], v[200:203], v[120:123]
	v_mfma_f32_16x16x32_bf16 v[112:115], v[176:179], v[208:211], v[112:115]
	v_mfma_f32_16x16x32_bf16 v[100:103], v[184:187], v[208:211], v[100:103]
	v_mfma_f32_16x16x32_bf16 v[96:99], v[176:179], v[216:219], v[96:99]
	v_mfma_f32_16x16x32_bf16 v[84:87], v[184:187], v[216:219], v[84:87]
	v_mfma_f32_16x16x32_bf16 v[80:83], v[176:179], v[224:227], v[80:83]
	v_mfma_f32_16x16x32_bf16 v[68:71], v[184:187], v[224:227], v[68:71]
	v_mfma_f32_16x16x32_bf16 v[128:131], v[180:183], v[204:207], v[128:131]
	v_mfma_f32_16x16x32_bf16 v[120:123], v[188:191], v[204:207], v[120:123]
	v_mfma_f32_16x16x32_bf16 v[112:115], v[180:183], v[212:215], v[112:115]
	v_mfma_f32_16x16x32_bf16 v[100:103], v[188:191], v[212:215], v[100:103]
	v_mfma_f32_16x16x32_bf16 v[96:99], v[180:183], v[220:223], v[96:99]
	v_mfma_f32_16x16x32_bf16 v[84:87], v[188:191], v[220:223], v[84:87]
	v_mfma_f32_16x16x32_bf16 v[80:83], v[180:183], v[228:231], v[80:83]
	v_mfma_f32_16x16x32_bf16 v[68:71], v[188:191], v[228:231], v[68:71]
	s_setprio 0
	s_barrier
	s_add_i32 s24, s24, s20
	v_lshl_add_u64 v[192:193], v[192:193], 0, s[26:27]
	s_mov_b32 m0, s24
	ds_read_b128 v[200:203], v147 offset:49152
	ds_read_b128 v[204:207], v147 offset:50176
	ds_read_b128 v[208:211], v147 offset:51200
	ds_read_b128 v[212:215], v147 offset:52224
	ds_read_b128 v[216:219], v147 offset:53248
	ds_read_b128 v[220:223], v147 offset:54272
	ds_read_b128 v[224:227], v147 offset:55296
	ds_read_b128 v[228:231], v147 offset:56320
	global_load_lds_dwordx4 v[192:193], off
	s_add_i32 m0, s24, 0x2000
	s_add_u32 s14, s14, 0x40080
	v_lshl_add_u64 v[192:193], v[232:233], 0, s[26:27]
	s_addc_u32 s15, s15, 0
	s_add_i32 s24, s25, s20
	global_load_lds_dwordx4 v[192:193], off
	v_lshl_add_u64 v[192:193], s[14:15], 0, v[2:3]
	s_mov_b32 m0, s24
	s_nop 0
	global_load_lds_dwordx4 v[192:193], off
	v_lshl_add_u64 v[192:193], s[14:15], 0, v[0:1]
	s_add_i32 m0, s24, 0x2000
	s_nop 0
	global_load_lds_dwordx4 v[192:193], off
	v_lshl_add_u64 v[192:193], v[234:235], 0, s[26:27]
	s_mov_b32 m0, s36
	s_nop 0
	global_load_lds_dwordx4 v[192:193], off
	v_lshl_add_u64 v[192:193], v[236:237], 0, s[26:27]
	s_mov_b32 m0, s48
	s_nop 0
	global_load_lds_dwordx4 v[192:193], off
	s_waitcnt vmcnt(8)
	s_waitcnt lgkmcnt(0)
	v_mfma_f32_16x16x32_bf16 v[60:63], v[140:143], v[200:203], v[60:63]
	v_mfma_f32_16x16x32_bf16 v[56:59], v[152:155], v[200:203], v[56:59]
	v_mfma_f32_16x16x32_bf16 v[44:47], v[140:143], v[208:211], v[44:47]
	v_mfma_f32_16x16x32_bf16 v[40:43], v[152:155], v[208:211], v[40:43]
	v_mfma_f32_16x16x32_bf16 v[28:31], v[140:143], v[216:219], v[28:31]
	v_mfma_f32_16x16x32_bf16 v[24:27], v[152:155], v[216:219], v[24:27]
	v_mfma_f32_16x16x32_bf16 v[12:15], v[140:143], v[224:227], v[12:15]
	v_mfma_f32_16x16x32_bf16 v[4:7], v[152:155], v[224:227], v[4:7]
	s_barrier
	s_setprio 1
	s_waitcnt lgkmcnt(0)
	v_mfma_f32_16x16x32_bf16 v[60:63], v[148:151], v[204:207], v[60:63]
	v_mfma_f32_16x16x32_bf16 v[56:59], v[172:175], v[204:207], v[56:59]
	v_mfma_f32_16x16x32_bf16 v[44:47], v[148:151], v[212:215], v[44:47]
	v_mfma_f32_16x16x32_bf16 v[40:43], v[172:175], v[212:215], v[40:43]
	v_mfma_f32_16x16x32_bf16 v[28:31], v[148:151], v[220:223], v[28:31]
	v_mfma_f32_16x16x32_bf16 v[24:27], v[172:175], v[220:223], v[24:27]
	v_mfma_f32_16x16x32_bf16 v[12:15], v[148:151], v[228:231], v[12:15]
	v_mfma_f32_16x16x32_bf16 v[4:7], v[172:175], v[228:231], v[4:7]
	s_setprio 0
	s_setprio 1
	v_mfma_f32_16x16x32_bf16 v[64:67], v[176:179], v[200:203], v[64:67]
	v_mfma_f32_16x16x32_bf16 v[52:55], v[184:187], v[200:203], v[52:55]
	v_mfma_f32_16x16x32_bf16 v[48:51], v[176:179], v[208:211], v[48:51]
	v_mfma_f32_16x16x32_bf16 v[36:39], v[184:187], v[208:211], v[36:39]
	v_mfma_f32_16x16x32_bf16 v[32:35], v[176:179], v[216:219], v[32:35]
	v_mfma_f32_16x16x32_bf16 v[20:23], v[184:187], v[216:219], v[20:23]
	v_mfma_f32_16x16x32_bf16 v[16:19], v[176:179], v[224:227], v[16:19]
	v_mfma_f32_16x16x32_bf16 v[8:11], v[184:187], v[224:227], v[8:11]
	v_mfma_f32_16x16x32_bf16 v[64:67], v[180:183], v[204:207], v[64:67]
	v_mfma_f32_16x16x32_bf16 v[52:55], v[188:191], v[204:207], v[52:55]
	v_mfma_f32_16x16x32_bf16 v[48:51], v[180:183], v[212:215], v[48:51]
	v_mfma_f32_16x16x32_bf16 v[36:39], v[188:191], v[212:215], v[36:39]
	v_mfma_f32_16x16x32_bf16 v[32:35], v[180:183], v[220:223], v[32:35]
	v_mfma_f32_16x16x32_bf16 v[20:23], v[188:191], v[220:223], v[20:23]
	v_mfma_f32_16x16x32_bf16 v[16:19], v[180:183], v[228:231], v[16:19]
	v_mfma_f32_16x16x32_bf16 v[8:11], v[188:191], v[228:231], v[8:11]
	s_setprio 0
	s_barrier
	s_add_i32 s63, s63, 2
	s_add_u32 s60, s60, 0x100
	s_addc_u32 s61, s61, 0
	s_add_u32 s42, s42, 0x100
	s_addc_u32 s43, s43, 0
	s_cmp_gt_u32 s63, 13
	s_cbranch_scc0 .LBB0_960
	s_branch .Lpeel_exit_G3
.LBB0_960:
	s_add_u32 s14, s42, 0xfffc0080
	s_addc_u32 s15, s43, -1
	s_add_i32 s24, 0, 0x10000
	s_cmp_eq_u32 s63, 12
	s_cselect_b32 s47, s29, s15
	s_cselect_b32 s46, s54, s14
	s_cselect_b32 s15, s13, s61
	s_cselect_b32 s14, s55, s60
	s_add_i32 s25, 0, 0x14000
	v_add_u32_e32 v172, s24, v145
	v_add_u32_e32 v188, s25, v145
	ds_read_b128 v[140:143], v172
	ds_read_b128 v[148:151], v172 offset:1024
	ds_read_b128 v[152:155], v172 offset:2048
	ds_read_b128 v[172:175], v172 offset:3072
	ds_read_b128 v[176:179], v188
	ds_read_b128 v[180:183], v188 offset:1024
	ds_read_b128 v[184:187], v188 offset:2048
	ds_read_b128 v[188:191], v188 offset:3072
	v_lshl_add_u64 v[192:193], s[42:43], 0, v[138:139]
	s_add_i32 m0, s21, 0xc000
	ds_read_b128 v[200:203], v147
	ds_read_b128 v[204:207], v147 offset:1024
	ds_read_b128 v[208:211], v147 offset:2048
	ds_read_b128 v[212:215], v147 offset:3072
	ds_read_b128 v[216:219], v147 offset:4096
	ds_read_b128 v[220:223], v147 offset:5120
	ds_read_b128 v[224:227], v147 offset:6144
	ds_read_b128 v[228:231], v147 offset:7168
	global_load_lds_dwordx4 v[192:193], off
	v_lshl_add_u64 v[192:193], s[42:43], 0, v[136:137]
	s_add_i32 m0, s21, 0xe000
	s_nop 0
	global_load_lds_dwordx4 v[192:193], off
	s_waitcnt vmcnt(8)
	s_waitcnt lgkmcnt(0)
	v_mfma_f32_16x16x32_bf16 v[124:127], v[140:143], v[200:203], v[124:127]
	v_mfma_f32_16x16x32_bf16 v[116:119], v[152:155], v[200:203], v[116:119]
	v_mfma_f32_16x16x32_bf16 v[108:111], v[140:143], v[208:211], v[108:111]
	v_mfma_f32_16x16x32_bf16 v[104:107], v[152:155], v[208:211], v[104:107]
	v_mfma_f32_16x16x32_bf16 v[92:95], v[140:143], v[216:219], v[92:95]
	v_mfma_f32_16x16x32_bf16 v[88:91], v[152:155], v[216:219], v[88:91]
	v_mfma_f32_16x16x32_bf16 v[76:79], v[140:143], v[224:227], v[76:79]
	v_mfma_f32_16x16x32_bf16 v[72:75], v[152:155], v[224:227], v[72:75]
	s_barrier
	s_setprio 1
	s_waitcnt lgkmcnt(0)
	v_mfma_f32_16x16x32_bf16 v[124:127], v[148:151], v[204:207], v[124:127]
	v_mfma_f32_16x16x32_bf16 v[116:119], v[172:175], v[204:207], v[116:119]
	v_mfma_f32_16x16x32_bf16 v[108:111], v[148:151], v[212:215], v[108:111]
	v_mfma_f32_16x16x32_bf16 v[104:107], v[172:175], v[212:215], v[104:107]
	v_mfma_f32_16x16x32_bf16 v[92:95], v[148:151], v[220:223], v[92:95]
	v_mfma_f32_16x16x32_bf16 v[88:91], v[172:175], v[220:223], v[88:91]
	v_mfma_f32_16x16x32_bf16 v[76:79], v[148:151], v[228:231], v[76:79]
	v_mfma_f32_16x16x32_bf16 v[72:75], v[172:175], v[228:231], v[72:75]
	s_setprio 0
	s_setprio 1
	v_mfma_f32_16x16x32_bf16 v[128:131], v[176:179], v[200:203], v[128:131]
	v_mfma_f32_16x16x32_bf16 v[120:123], v[184:187], v[200:203], v[120:123]
	v_mfma_f32_16x16x32_bf16 v[112:115], v[176:179], v[208:211], v[112:115]
	v_mfma_f32_16x16x32_bf16 v[100:103], v[184:187], v[208:211], v[100:103]
	v_mfma_f32_16x16x32_bf16 v[96:99], v[176:179], v[216:219], v[96:99]
	v_mfma_f32_16x16x32_bf16 v[84:87], v[184:187], v[216:219], v[84:87]
	v_mfma_f32_16x16x32_bf16 v[80:83], v[176:179], v[224:227], v[80:83]
	v_mfma_f32_16x16x32_bf16 v[68:71], v[184:187], v[224:227], v[68:71]
	v_mfma_f32_16x16x32_bf16 v[128:131], v[180:183], v[204:207], v[128:131]
	v_mfma_f32_16x16x32_bf16 v[120:123], v[188:191], v[204:207], v[120:123]
	v_mfma_f32_16x16x32_bf16 v[112:115], v[180:183], v[212:215], v[112:115]
	v_mfma_f32_16x16x32_bf16 v[100:103], v[188:191], v[212:215], v[100:103]
	v_mfma_f32_16x16x32_bf16 v[96:99], v[180:183], v[220:223], v[96:99]
	v_mfma_f32_16x16x32_bf16 v[84:87], v[188:191], v[220:223], v[84:87]
	v_mfma_f32_16x16x32_bf16 v[80:83], v[180:183], v[228:231], v[80:83]
	v_mfma_f32_16x16x32_bf16 v[68:71], v[188:191], v[228:231], v[68:71]
	s_setprio 0
	s_barrier
	s_add_i32 s24, s24, s20
	v_lshl_add_u64 v[192:193], s[14:15], 0, v[2:3]
	s_mov_b32 m0, s24
	ds_read_b128 v[200:203], v147 offset:16384
	ds_read_b128 v[204:207], v147 offset:17408
	ds_read_b128 v[208:211], v147 offset:18432
	ds_read_b128 v[212:215], v147 offset:19456
	ds_read_b128 v[216:219], v147 offset:20480
	ds_read_b128 v[220:223], v147 offset:21504
	ds_read_b128 v[224:227], v147 offset:22528
	ds_read_b128 v[228:231], v147 offset:23552
	global_load_lds_dwordx4 v[192:193], off
	s_add_i32 m0, s24, 0x2000
	s_add_u32 s64, s14, 0x40000
	v_lshl_add_u64 v[232:233], s[14:15], 0, v[0:1]
	s_addc_u32 s65, s15, 0
	s_add_i32 s24, s25, s20
	global_load_lds_dwordx4 v[232:233], off
	v_lshl_add_u64 v[234:235], s[64:65], 0, v[2:3]
	s_mov_b32 m0, s24
	v_lshl_add_u64 v[236:237], s[46:47], 0, v[132:133]
	global_load_lds_dwordx4 v[234:235], off
	v_lshl_add_u64 v[234:235], s[64:65], 0, v[0:1]
	s_add_i32 m0, s24, 0x2000
	s_nop 0
	global_load_lds_dwordx4 v[234:235], off
	v_lshl_add_u64 v[234:235], s[46:47], 0, v[134:135]
	s_mov_b32 m0, s21
	s_nop 0
	global_load_lds_dwordx4 v[234:235], off
	s_mov_b32 m0, s22
	s_nop 0
	global_load_lds_dwordx4 v[236:237], off
	s_waitcnt vmcnt(8)
	s_waitcnt lgkmcnt(0)
	v_mfma_f32_16x16x32_bf16 v[60:63], v[140:143], v[200:203], v[60:63]
	v_mfma_f32_16x16x32_bf16 v[56:59], v[152:155], v[200:203], v[56:59]
	v_mfma_f32_16x16x32_bf16 v[44:47], v[140:143], v[208:211], v[44:47]
	v_mfma_f32_16x16x32_bf16 v[40:43], v[152:155], v[208:211], v[40:43]
	v_mfma_f32_16x16x32_bf16 v[28:31], v[140:143], v[216:219], v[28:31]
	v_mfma_f32_16x16x32_bf16 v[24:27], v[152:155], v[216:219], v[24:27]
	v_mfma_f32_16x16x32_bf16 v[12:15], v[140:143], v[224:227], v[12:15]
	v_mfma_f32_16x16x32_bf16 v[4:7], v[152:155], v[224:227], v[4:7]
	s_barrier
	s_setprio 1
	s_waitcnt lgkmcnt(0)
	v_mfma_f32_16x16x32_bf16 v[60:63], v[148:151], v[204:207], v[60:63]
	v_mfma_f32_16x16x32_bf16 v[56:59], v[172:175], v[204:207], v[56:59]
	v_mfma_f32_16x16x32_bf16 v[44:47], v[148:151], v[212:215], v[44:47]
	v_mfma_f32_16x16x32_bf16 v[40:43], v[172:175], v[212:215], v[40:43]
	v_mfma_f32_16x16x32_bf16 v[28:31], v[148:151], v[220:223], v[28:31]
	v_mfma_f32_16x16x32_bf16 v[24:27], v[172:175], v[220:223], v[24:27]
	v_mfma_f32_16x16x32_bf16 v[12:15], v[148:151], v[228:231], v[12:15]
	v_mfma_f32_16x16x32_bf16 v[4:7], v[172:175], v[228:231], v[4:7]
	s_setprio 0
	s_setprio 1
	v_mfma_f32_16x16x32_bf16 v[64:67], v[176:179], v[200:203], v[64:67]
	v_mfma_f32_16x16x32_bf16 v[52:55], v[184:187], v[200:203], v[52:55]
	v_mfma_f32_16x16x32_bf16 v[48:51], v[176:179], v[208:211], v[48:51]
	v_mfma_f32_16x16x32_bf16 v[36:39], v[184:187], v[208:211], v[36:39]
	v_mfma_f32_16x16x32_bf16 v[32:35], v[176:179], v[216:219], v[32:35]
	v_mfma_f32_16x16x32_bf16 v[20:23], v[184:187], v[216:219], v[20:23]
	v_mfma_f32_16x16x32_bf16 v[16:19], v[176:179], v[224:227], v[16:19]
	v_mfma_f32_16x16x32_bf16 v[8:11], v[184:187], v[224:227], v[8:11]
	v_mfma_f32_16x16x32_bf16 v[64:67], v[180:183], v[204:207], v[64:67]
	v_mfma_f32_16x16x32_bf16 v[52:55], v[188:191], v[204:207], v[52:55]
	v_mfma_f32_16x16x32_bf16 v[48:51], v[180:183], v[212:215], v[48:51]
	v_mfma_f32_16x16x32_bf16 v[36:39], v[188:191], v[212:215], v[36:39]
	v_mfma_f32_16x16x32_bf16 v[32:35], v[180:183], v[220:223], v[32:35]
	v_mfma_f32_16x16x32_bf16 v[20:23], v[188:191], v[220:223], v[20:23]
	v_mfma_f32_16x16x32_bf16 v[16:19], v[180:183], v[228:231], v[16:19]
	v_mfma_f32_16x16x32_bf16 v[8:11], v[188:191], v[228:231], v[8:11]
	s_setprio 0
	s_barrier
	s_add_i32 s24, 0, 0x18000
	s_add_i32 s25, 0, 0x1c000
	v_add_u32_e32 v172, s24, v145
	v_add_u32_e32 v188, s25, v145
	ds_read_b128 v[140:143], v172
	ds_read_b128 v[148:151], v172 offset:1024
	ds_read_b128 v[152:155], v172 offset:2048
	ds_read_b128 v[172:175], v172 offset:3072
	ds_read_b128 v[176:179], v188
	ds_read_b128 v[180:183], v188 offset:1024
	ds_read_b128 v[184:187], v188 offset:2048
	ds_read_b128 v[188:191], v188 offset:3072
	s_add_u32 s46, s46, 0x40000
	s_addc_u32 s47, s47, 0
	s_mov_b32 m0, s23
	v_lshl_add_u64 v[238:239], s[46:47], 0, v[134:135]
	ds_read_b128 v[200:203], v147 offset:32768
	ds_read_b128 v[204:207], v147 offset:33792
	ds_read_b128 v[208:211], v147 offset:34816
	ds_read_b128 v[212:215], v147 offset:35840
	ds_read_b128 v[216:219], v147 offset:36864
	ds_read_b128 v[220:223], v147 offset:37888
	ds_read_b128 v[224:227], v147 offset:38912
	ds_read_b128 v[228:231], v147 offset:39936
	global_load_lds_dwordx4 v[238:239], off
	v_lshl_add_u64 v[238:239], s[46:47], 0, v[132:133]
	s_mov_b32 m0, s45
	s_nop 0
	global_load_lds_dwordx4 v[238:239], off
	s_waitcnt vmcnt(8)
	s_waitcnt lgkmcnt(0)
	v_mfma_f32_16x16x32_bf16 v[124:127], v[140:143], v[200:203], v[124:127]
	v_mfma_f32_16x16x32_bf16 v[116:119], v[152:155], v[200:203], v[116:119]
	v_mfma_f32_16x16x32_bf16 v[108:111], v[140:143], v[208:211], v[108:111]
	v_mfma_f32_16x16x32_bf16 v[104:107], v[152:155], v[208:211], v[104:107]
	v_mfma_f32_16x16x32_bf16 v[92:95], v[140:143], v[216:219], v[92:95]
	v_mfma_f32_16x16x32_bf16 v[88:91], v[152:155], v[216:219], v[88:91]
	v_mfma_f32_16x16x32_bf16 v[76:79], v[140:143], v[224:227], v[76:79]
	v_mfma_f32_16x16x32_bf16 v[72:75], v[152:155], v[224:227], v[72:75]
	s_barrier
	s_setprio 1
	s_waitcnt lgkmcnt(0)
	v_mfma_f32_16x16x32_bf16 v[124:127], v[148:151], v[204:207], v[124:127]
	v_mfma_f32_16x16x32_bf16 v[116:119], v[172:175], v[204:207], v[116:119]
	v_mfma_f32_16x16x32_bf16 v[108:111], v[148:151], v[212:215], v[108:111]
	v_mfma_f32_16x16x32_bf16 v[104:107], v[172:175], v[212:215], v[104:107]
	v_mfma_f32_16x16x32_bf16 v[92:95], v[148:151], v[220:223], v[92:95]
	v_mfma_f32_16x16x32_bf16 v[88:91], v[172:175], v[220:223], v[88:91]
	v_mfma_f32_16x16x32_bf16 v[76:79], v[148:151], v[228:231], v[76:79]
	v_mfma_f32_16x16x32_bf16 v[72:75], v[172:175], v[228:231], v[72:75]
	s_setprio 0
	s_setprio 1
	v_mfma_f32_16x16x32_bf16 v[128:131], v[176:179], v[200:203], v[128:131]
	v_mfma_f32_16x16x32_bf16 v[120:123], v[184:187], v[200:203], v[120:123]
	v_mfma_f32_16x16x32_bf16 v[112:115], v[176:179], v[208:211], v[112:115]
	v_mfma_f32_16x16x32_bf16 v[100:103], v[184:187], v[208:211], v[100:103]
	v_mfma_f32_16x16x32_bf16 v[96:99], v[176:179], v[216:219], v[96:99]
	v_mfma_f32_16x16x32_bf16 v[84:87], v[184:187], v[216:219], v[84:87]
	v_mfma_f32_16x16x32_bf16 v[80:83], v[176:179], v[224:227], v[80:83]
	v_mfma_f32_16x16x32_bf16 v[68:71], v[184:187], v[224:227], v[68:71]
	v_mfma_f32_16x16x32_bf16 v[128:131], v[180:183], v[204:207], v[128:131]
	v_mfma_f32_16x16x32_bf16 v[120:123], v[188:191], v[204:207], v[120:123]
	v_mfma_f32_16x16x32_bf16 v[112:115], v[180:183], v[212:215], v[112:115]
	v_mfma_f32_16x16x32_bf16 v[100:103], v[188:191], v[212:215], v[100:103]
	v_mfma_f32_16x16x32_bf16 v[96:99], v[180:183], v[220:223], v[96:99]
	v_mfma_f32_16x16x32_bf16 v[84:87], v[188:191], v[220:223], v[84:87]
	v_mfma_f32_16x16x32_bf16 v[80:83], v[180:183], v[228:231], v[80:83]
	v_mfma_f32_16x16x32_bf16 v[68:71], v[188:191], v[228:231], v[68:71]
	s_setprio 0
	s_barrier
	s_add_i32 s24, s24, s20
	v_lshl_add_u64 v[192:193], v[192:193], 0, s[26:27]
	s_mov_b32 m0, s24
	ds_read_b128 v[200:203], v147 offset:49152
	ds_read_b128 v[204:207], v147 offset:50176
	ds_read_b128 v[208:211], v147 offset:51200
	ds_read_b128 v[212:215], v147 offset:52224
	ds_read_b128 v[216:219], v147 offset:53248
	ds_read_b128 v[220:223], v147 offset:54272
	ds_read_b128 v[224:227], v147 offset:55296
	ds_read_b128 v[228:231], v147 offset:56320
	global_load_lds_dwordx4 v[192:193], off
	s_add_i32 m0, s24, 0x2000
	s_add_u32 s14, s14, 0x40080
	v_lshl_add_u64 v[192:193], v[232:233], 0, s[26:27]
	s_addc_u32 s15, s15, 0
	s_add_i32 s24, s25, s20
	global_load_lds_dwordx4 v[192:193], off
	v_lshl_add_u64 v[192:193], s[14:15], 0, v[2:3]
	s_mov_b32 m0, s24
	s_nop 0
	global_load_lds_dwordx4 v[192:193], off
	v_lshl_add_u64 v[192:193], s[14:15], 0, v[0:1]
	s_add_i32 m0, s24, 0x2000
	s_nop 0
	global_load_lds_dwordx4 v[192:193], off
	v_lshl_add_u64 v[192:193], v[234:235], 0, s[26:27]
	s_mov_b32 m0, s36
	s_nop 0
	global_load_lds_dwordx4 v[192:193], off
	v_lshl_add_u64 v[192:193], v[236:237], 0, s[26:27]
	s_mov_b32 m0, s48
	s_nop 0
	global_load_lds_dwordx4 v[192:193], off
	s_waitcnt vmcnt(8)
	s_waitcnt lgkmcnt(0)
	v_mfma_f32_16x16x32_bf16 v[60:63], v[140:143], v[200:203], v[60:63]
	v_mfma_f32_16x16x32_bf16 v[56:59], v[152:155], v[200:203], v[56:59]
	v_mfma_f32_16x16x32_bf16 v[44:47], v[140:143], v[208:211], v[44:47]
	v_mfma_f32_16x16x32_bf16 v[40:43], v[152:155], v[208:211], v[40:43]
	v_mfma_f32_16x16x32_bf16 v[28:31], v[140:143], v[216:219], v[28:31]
	v_mfma_f32_16x16x32_bf16 v[24:27], v[152:155], v[216:219], v[24:27]
	v_mfma_f32_16x16x32_bf16 v[12:15], v[140:143], v[224:227], v[12:15]
	v_mfma_f32_16x16x32_bf16 v[4:7], v[152:155], v[224:227], v[4:7]
	s_barrier
	s_setprio 1
	s_waitcnt lgkmcnt(0)
	v_mfma_f32_16x16x32_bf16 v[60:63], v[148:151], v[204:207], v[60:63]
	v_mfma_f32_16x16x32_bf16 v[56:59], v[172:175], v[204:207], v[56:59]
	v_mfma_f32_16x16x32_bf16 v[44:47], v[148:151], v[212:215], v[44:47]
	v_mfma_f32_16x16x32_bf16 v[40:43], v[172:175], v[212:215], v[40:43]
	v_mfma_f32_16x16x32_bf16 v[28:31], v[148:151], v[220:223], v[28:31]
	v_mfma_f32_16x16x32_bf16 v[24:27], v[172:175], v[220:223], v[24:27]
	v_mfma_f32_16x16x32_bf16 v[12:15], v[148:151], v[228:231], v[12:15]
	v_mfma_f32_16x16x32_bf16 v[4:7], v[172:175], v[228:231], v[4:7]
	s_setprio 0
	s_setprio 1
	v_mfma_f32_16x16x32_bf16 v[64:67], v[176:179], v[200:203], v[64:67]
	v_mfma_f32_16x16x32_bf16 v[52:55], v[184:187], v[200:203], v[52:55]
	v_mfma_f32_16x16x32_bf16 v[48:51], v[176:179], v[208:211], v[48:51]
	v_mfma_f32_16x16x32_bf16 v[36:39], v[184:187], v[208:211], v[36:39]
	v_mfma_f32_16x16x32_bf16 v[32:35], v[176:179], v[216:219], v[32:35]
	v_mfma_f32_16x16x32_bf16 v[20:23], v[184:187], v[216:219], v[20:23]
	v_mfma_f32_16x16x32_bf16 v[16:19], v[176:179], v[224:227], v[16:19]
	v_mfma_f32_16x16x32_bf16 v[8:11], v[184:187], v[224:227], v[8:11]
	v_mfma_f32_16x16x32_bf16 v[64:67], v[180:183], v[204:207], v[64:67]
	v_mfma_f32_16x16x32_bf16 v[52:55], v[188:191], v[204:207], v[52:55]
	v_mfma_f32_16x16x32_bf16 v[48:51], v[180:183], v[212:215], v[48:51]
	v_mfma_f32_16x16x32_bf16 v[36:39], v[188:191], v[212:215], v[36:39]
	v_mfma_f32_16x16x32_bf16 v[32:35], v[180:183], v[220:223], v[32:35]
	v_mfma_f32_16x16x32_bf16 v[20:23], v[188:191], v[220:223], v[20:23]
	v_mfma_f32_16x16x32_bf16 v[16:19], v[180:183], v[228:231], v[16:19]
	v_mfma_f32_16x16x32_bf16 v[8:11], v[188:191], v[228:231], v[8:11]
	s_setprio 0
	s_barrier
	s_add_i32 s63, s63, 2
	s_add_u32 s60, s60, 0x100
	s_addc_u32 s61, s61, 0
	s_add_u32 s42, s42, 0x100
	s_addc_u32 s43, s43, 0
	s_cmp_gt_u32 s63, 13
	s_cbranch_scc0 .LBB0_960
